# phase 0: nt hint on all input loads (weight transposes and sample caches too)
# speedup vs baseline: 1.0110x; 1.0027x over previous
; __device__ __forceinline__ void tconv_wave(const float* __restrict__ src, int ldsrc, int k0, int nsrc0, int nvalid,
;                                            u16* __restrict__ dst, int K, int ndst0, const float* __restrict__ gain, float* smw, int lane, int permg) {
; #pragma unroll 1
;   for (int kb = 0; kb < 64; kb += 32) {
;     float v[32];
; #pragma unroll
;     for (int i = 0; i < 32; i++) {
;       float t = 0.f;
;       if (lane < nvalid) {
;         t = src[(size_t)(k0 + kb + i) * ldsrc + nsrc0 + lane];
;         if (gain) t *= gain[k0 + kb + i];
;       }
;       v[i] = t;
;     }
.LBB0_32:
	v_or_b32_e32 v22, s35, v2
	v_ashrrev_i32_e32 v23, 31, v22
	v_mov_b32_e32 v3, 0
	v_mul_lo_u32 v6, v16, v23
	v_mov_b32_e32 v5, 0
	s_and_saveexec_b64 s[42:43], s[38:39]
	s_cbranch_execz .LBB0_36
	v_mul_lo_u32 v5, v17, v22
	v_mad_u64_u32 v[28:29], s[44:45], v16, v22, 0
	v_add3_u32 v29, v29, v6, v5
	v_lshl_add_u64 v[28:29], v[28:29], 2, v[20:21]
	global_load_dword v5, v[28:29], off nt
	s_and_saveexec_b64 s[44:45], s[6:7]
	s_cbranch_execz .LBB0_35
	v_lshl_add_u64 v[28:29], v[22:23], 2, v[14:15]
	global_load_dword v64, v[28:29], off nt

; __device__ __forceinline__ void tconv_wave(const float* __restrict__ src, int ldsrc, int k0, int nsrc0, int nvalid,
;                                            u16* __restrict__ dst, int K, int ndst0, const float* __restrict__ gain, float* smw, int lane, int permg) {
;     ...
;     for (int i = 0; i < 32; i++) {
;       float t = 0.f;
;       if (lane < nvalid) {
;         t = src[(size_t)(k0 + kb + i) * ldsrc + nsrc0 + lane];
;         if (gain) t *= gain[k0 + kb + i];
;       }
;       v[i] = t;
;     }
.LBB0_36:
	s_or_b64 exec, exec, s[42:43]
	s_and_saveexec_b64 s[42:43], s[38:39]
	s_cbranch_execz .LBB0_40
	v_or_b32_e32 v3, 1, v22
	v_mul_lo_u32 v30, v17, v3
	v_mad_u64_u32 v[28:29], s[44:45], v16, v3, 0
	v_add3_u32 v29, v29, v6, v30
	v_lshl_add_u64 v[28:29], v[28:29], 2, v[20:21]
	global_load_dword v3, v[28:29], off nt
	s_and_saveexec_b64 s[44:45], s[6:7]
	s_cbranch_execz .LBB0_39
	v_lshl_add_u64 v[28:29], v[22:23], 2, v[14:15]
	global_load_dword v65, v[28:29], off offset:4 nt

; __device__ __forceinline__ void tconv_wave(const float* __restrict__ src, int ldsrc, int k0, int nsrc0, int nvalid,
;                                            u16* __restrict__ dst, int K, int ndst0, const float* __restrict__ gain, float* smw, int lane, int permg) {
;     ...
;     for (int i = 0; i < 32; i++) {
;       float t = 0.f;
;       if (lane < nvalid) {
;         t = src[(size_t)(k0 + kb + i) * ldsrc + nsrc0 + lane];
;         if (gain) t *= gain[k0 + kb + i];
;       }
;       v[i] = t;
;     }
.LBB0_40:
	s_or_b64 exec, exec, s[42:43]
	v_mov_b32_e32 v28, 0
	v_mov_b32_e32 v29, 0
	s_and_saveexec_b64 s[42:43], s[38:39]
	s_cbranch_execz .LBB0_44
	v_or_b32_e32 v29, 2, v22
	v_mul_lo_u32 v32, v17, v29
	v_mad_u64_u32 v[30:31], s[44:45], v16, v29, 0
	v_add3_u32 v31, v31, v6, v32
	v_lshl_add_u64 v[30:31], v[30:31], 2, v[20:21]
	global_load_dword v29, v[30:31], off nt
	s_and_saveexec_b64 s[44:45], s[6:7]
	s_cbranch_execz .LBB0_43
	v_lshl_add_u64 v[30:31], v[22:23], 2, v[14:15]
	global_load_dword v66, v[30:31], off offset:8 nt

; __device__ __forceinline__ void tconv_wave(const float* __restrict__ src, int ldsrc, int k0, int nsrc0, int nvalid,
;                                            u16* __restrict__ dst, int K, int ndst0, const float* __restrict__ gain, float* smw, int lane, int permg) {
;     ...
;     for (int i = 0; i < 32; i++) {
;       float t = 0.f;
;       if (lane < nvalid) {
;         t = src[(size_t)(k0 + kb + i) * ldsrc + nsrc0 + lane];
;         if (gain) t *= gain[k0 + kb + i];
;       }
;       v[i] = t;
;     }
.LBB0_44:
	s_or_b64 exec, exec, s[42:43]
	s_and_saveexec_b64 s[42:43], s[38:39]
	s_cbranch_execz .LBB0_48
	v_or_b32_e32 v28, 3, v22
	v_mul_lo_u32 v32, v17, v28
	v_mad_u64_u32 v[30:31], s[44:45], v16, v28, 0
	v_add3_u32 v31, v31, v6, v32
	v_lshl_add_u64 v[30:31], v[30:31], 2, v[20:21]
	global_load_dword v28, v[30:31], off nt
	s_and_saveexec_b64 s[44:45], s[6:7]
	s_cbranch_execz .LBB0_47
	v_lshl_add_u64 v[30:31], v[22:23], 2, v[14:15]
	global_load_dword v67, v[30:31], off offset:12 nt

; __device__ __forceinline__ void tconv_wave(const float* __restrict__ src, int ldsrc, int k0, int nsrc0, int nvalid,
;                                            u16* __restrict__ dst, int K, int ndst0, const float* __restrict__ gain, float* smw, int lane, int permg) {
;     ...
;     for (int i = 0; i < 32; i++) {
;       float t = 0.f;
;       if (lane < nvalid) {
;         t = src[(size_t)(k0 + kb + i) * ldsrc + nsrc0 + lane];
;         if (gain) t *= gain[k0 + kb + i];
;       }
;       v[i] = t;
;     }
.LBB0_48:
	s_or_b64 exec, exec, s[42:43]
	v_mov_b32_e32 v30, 0
	v_mov_b32_e32 v31, 0
	s_and_saveexec_b64 s[42:43], s[38:39]
	s_cbranch_execz .LBB0_52
	v_or_b32_e32 v31, 4, v22
	v_mul_lo_u32 v35, v17, v31
	v_mad_u64_u32 v[32:33], s[44:45], v16, v31, 0
	v_add3_u32 v33, v33, v6, v35
	v_lshl_add_u64 v[32:33], v[32:33], 2, v[20:21]
	global_load_dword v31, v[32:33], off nt
	s_and_saveexec_b64 s[44:45], s[6:7]
	s_cbranch_execz .LBB0_51
	v_lshl_add_u64 v[32:33], v[22:23], 2, v[14:15]
	global_load_dword v68, v[32:33], off offset:16 nt

; __device__ __forceinline__ void tconv_wave(const float* __restrict__ src, int ldsrc, int k0, int nsrc0, int nvalid,
;                                            u16* __restrict__ dst, int K, int ndst0, const float* __restrict__ gain, float* smw, int lane, int permg) {
;     ...
;     for (int i = 0; i < 32; i++) {
;       float t = 0.f;
;       if (lane < nvalid) {
;         t = src[(size_t)(k0 + kb + i) * ldsrc + nsrc0 + lane];
;         if (gain) t *= gain[k0 + kb + i];
;       }
;       v[i] = t;
;     }
.LBB0_52:
	s_or_b64 exec, exec, s[42:43]
	s_and_saveexec_b64 s[42:43], s[38:39]
	s_cbranch_execz .LBB0_56
	v_or_b32_e32 v30, 5, v22
	v_mul_lo_u32 v35, v17, v30
	v_mad_u64_u32 v[32:33], s[44:45], v16, v30, 0
	v_add3_u32 v33, v33, v6, v35
	v_lshl_add_u64 v[32:33], v[32:33], 2, v[20:21]
	global_load_dword v30, v[32:33], off nt
	s_and_saveexec_b64 s[44:45], s[6:7]
	s_cbranch_execz .LBB0_55
	v_lshl_add_u64 v[32:33], v[22:23], 2, v[14:15]
	global_load_dword v69, v[32:33], off offset:20 nt

; __device__ __forceinline__ void tconv_wave(const float* __restrict__ src, int ldsrc, int k0, int nsrc0, int nvalid,
;                                            u16* __restrict__ dst, int K, int ndst0, const float* __restrict__ gain, float* smw, int lane, int permg) {
;     ...
;     for (int i = 0; i < 32; i++) {
;       float t = 0.f;
;       if (lane < nvalid) {
;         t = src[(size_t)(k0 + kb + i) * ldsrc + nsrc0 + lane];
;         if (gain) t *= gain[k0 + kb + i];
;       }
;       v[i] = t;
;     }
.LBB0_56:
	s_or_b64 exec, exec, s[42:43]
	v_mov_b32_e32 v32, 0
	v_mov_b32_e32 v33, 0
	s_and_saveexec_b64 s[42:43], s[38:39]
	s_cbranch_execz .LBB0_60
	v_or_b32_e32 v33, 6, v22
	v_mul_lo_u32 v35, v17, v33
	v_mad_u64_u32 v[36:37], s[44:45], v16, v33, 0
	v_add3_u32 v37, v37, v6, v35
	v_lshl_add_u64 v[36:37], v[36:37], 2, v[20:21]
	global_load_dword v33, v[36:37], off nt
	s_and_saveexec_b64 s[44:45], s[6:7]
	s_cbranch_execz .LBB0_59
	v_lshl_add_u64 v[36:37], v[22:23], 2, v[14:15]
	global_load_dword v70, v[36:37], off offset:24 nt

; __device__ __forceinline__ void tconv_wave(const float* __restrict__ src, int ldsrc, int k0, int nsrc0, int nvalid,
;                                            u16* __restrict__ dst, int K, int ndst0, const float* __restrict__ gain, float* smw, int lane, int permg) {
;     ...
;     for (int i = 0; i < 32; i++) {
;       float t = 0.f;
;       if (lane < nvalid) {
;         t = src[(size_t)(k0 + kb + i) * ldsrc + nsrc0 + lane];
;         if (gain) t *= gain[k0 + kb + i];
;       }
;       v[i] = t;
;     }
.LBB0_60:
	s_or_b64 exec, exec, s[42:43]
	s_and_saveexec_b64 s[42:43], s[38:39]
	s_cbranch_execz .LBB0_64
	v_or_b32_e32 v32, 7, v22
	v_mul_lo_u32 v35, v17, v32
	v_mad_u64_u32 v[36:37], s[44:45], v16, v32, 0
	v_add3_u32 v37, v37, v6, v35
	v_lshl_add_u64 v[36:37], v[36:37], 2, v[20:21]
	global_load_dword v32, v[36:37], off nt
	s_and_saveexec_b64 s[44:45], s[6:7]
	s_cbranch_execz .LBB0_63
	v_lshl_add_u64 v[36:37], v[22:23], 2, v[14:15]
	global_load_dword v71, v[36:37], off offset:28 nt

; __device__ __forceinline__ void tconv_wave(const float* __restrict__ src, int ldsrc, int k0, int nsrc0, int nvalid,
;                                            u16* __restrict__ dst, int K, int ndst0, const float* __restrict__ gain, float* smw, int lane, int permg) {
;     ...
;     for (int i = 0; i < 32; i++) {
;       float t = 0.f;
;       if (lane < nvalid) {
;         t = src[(size_t)(k0 + kb + i) * ldsrc + nsrc0 + lane];
;         if (gain) t *= gain[k0 + kb + i];
;       }
;       v[i] = t;
;     }
.LBB0_64:
	s_or_b64 exec, exec, s[42:43]
	v_mov_b32_e32 v35, 0
	v_mov_b32_e32 v36, 0
	s_and_saveexec_b64 s[42:43], s[38:39]
	s_cbranch_execz .LBB0_68
	v_or_b32_e32 v36, 8, v22
	v_mul_lo_u32 v38, v17, v36
	v_mad_u64_u32 v[36:37], s[44:45], v16, v36, 0
	v_add3_u32 v37, v37, v6, v38
	v_lshl_add_u64 v[36:37], v[36:37], 2, v[20:21]
	global_load_dword v36, v[36:37], off nt
	s_and_saveexec_b64 s[44:45], s[6:7]
	s_cbranch_execz .LBB0_67
	v_lshl_add_u64 v[38:39], v[22:23], 2, v[14:15]
	global_load_dword v72, v[38:39], off offset:32 nt

; __device__ __forceinline__ void tconv_wave(const float* __restrict__ src, int ldsrc, int k0, int nsrc0, int nvalid,
;                                            u16* __restrict__ dst, int K, int ndst0, const float* __restrict__ gain, float* smw, int lane, int permg) {
;     ...
;     for (int i = 0; i < 32; i++) {
;       float t = 0.f;
;       if (lane < nvalid) {
;         t = src[(size_t)(k0 + kb + i) * ldsrc + nsrc0 + lane];
;         if (gain) t *= gain[k0 + kb + i];
;       }
;       v[i] = t;
;     }
.LBB0_68:
	s_or_b64 exec, exec, s[42:43]
	s_and_saveexec_b64 s[42:43], s[38:39]
	s_cbranch_execz .LBB0_72
	v_or_b32_e32 v35, 9, v22
	v_mul_lo_u32 v37, v17, v35
	v_mad_u64_u32 v[38:39], s[44:45], v16, v35, 0
	v_add3_u32 v39, v39, v6, v37
	v_lshl_add_u64 v[38:39], v[38:39], 2, v[20:21]
	global_load_dword v35, v[38:39], off nt
	s_and_saveexec_b64 s[44:45], s[6:7]
	s_cbranch_execz .LBB0_71
	v_lshl_add_u64 v[38:39], v[22:23], 2, v[14:15]
	global_load_dword v73, v[38:39], off offset:36 nt

; __device__ __forceinline__ void tconv_wave(const float* __restrict__ src, int ldsrc, int k0, int nsrc0, int nvalid,
;                                            u16* __restrict__ dst, int K, int ndst0, const float* __restrict__ gain, float* smw, int lane, int permg) {
;     ...
;     for (int i = 0; i < 32; i++) {
;       float t = 0.f;
;       if (lane < nvalid) {
;         t = src[(size_t)(k0 + kb + i) * ldsrc + nsrc0 + lane];
;         if (gain) t *= gain[k0 + kb + i];
;       }
;       v[i] = t;
;     }
.LBB0_72:
	s_or_b64 exec, exec, s[42:43]
	v_mov_b32_e32 v37, 0
	v_mov_b32_e32 v38, 0
	s_and_saveexec_b64 s[42:43], s[38:39]
	s_cbranch_execz .LBB0_76
	v_or_b32_e32 v38, 10, v22
	v_mul_lo_u32 v40, v17, v38
	v_mad_u64_u32 v[38:39], s[44:45], v16, v38, 0
	v_add3_u32 v39, v39, v6, v40
	v_lshl_add_u64 v[38:39], v[38:39], 2, v[20:21]
	global_load_dword v38, v[38:39], off nt
	s_and_saveexec_b64 s[44:45], s[6:7]
	s_cbranch_execz .LBB0_75
	v_lshl_add_u64 v[40:41], v[22:23], 2, v[14:15]
	global_load_dword v74, v[40:41], off offset:40 nt

; __device__ __forceinline__ void tconv_wave(const float* __restrict__ src, int ldsrc, int k0, int nsrc0, int nvalid,
;                                            u16* __restrict__ dst, int K, int ndst0, const float* __restrict__ gain, float* smw, int lane, int permg) {
;     ...
;     for (int i = 0; i < 32; i++) {
;       float t = 0.f;
;       if (lane < nvalid) {
;         t = src[(size_t)(k0 + kb + i) * ldsrc + nsrc0 + lane];
;         if (gain) t *= gain[k0 + kb + i];
;       }
;       v[i] = t;
;     }
.LBB0_76:
	s_or_b64 exec, exec, s[42:43]
	s_and_saveexec_b64 s[42:43], s[38:39]
	s_cbranch_execz .LBB0_80
	v_or_b32_e32 v37, 11, v22
	v_mul_lo_u32 v39, v17, v37
	v_mad_u64_u32 v[40:41], s[44:45], v16, v37, 0
	v_add3_u32 v41, v41, v6, v39
	v_lshl_add_u64 v[40:41], v[40:41], 2, v[20:21]
	global_load_dword v37, v[40:41], off nt
	s_and_saveexec_b64 s[44:45], s[6:7]
	s_cbranch_execz .LBB0_79
	v_lshl_add_u64 v[40:41], v[22:23], 2, v[14:15]
	global_load_dword v75, v[40:41], off offset:44 nt

; __device__ __forceinline__ void tconv_wave(const float* __restrict__ src, int ldsrc, int k0, int nsrc0, int nvalid,
;                                            u16* __restrict__ dst, int K, int ndst0, const float* __restrict__ gain, float* smw, int lane, int permg) {
;     ...
;     for (int i = 0; i < 32; i++) {
;       float t = 0.f;
;       if (lane < nvalid) {
;         t = src[(size_t)(k0 + kb + i) * ldsrc + nsrc0 + lane];
;         if (gain) t *= gain[k0 + kb + i];
;       }
;       v[i] = t;
;     }
.LBB0_80:
	s_or_b64 exec, exec, s[42:43]
	v_mov_b32_e32 v39, 0
	v_mov_b32_e32 v40, 0
	s_and_saveexec_b64 s[42:43], s[38:39]
	s_cbranch_execz .LBB0_84
	v_or_b32_e32 v40, 12, v22
	v_mul_lo_u32 v42, v17, v40
	v_mad_u64_u32 v[40:41], s[44:45], v16, v40, 0
	v_add3_u32 v41, v41, v6, v42
	v_lshl_add_u64 v[40:41], v[40:41], 2, v[20:21]
	global_load_dword v40, v[40:41], off nt
	s_and_saveexec_b64 s[44:45], s[6:7]
	s_cbranch_execz .LBB0_83
	v_lshl_add_u64 v[42:43], v[22:23], 2, v[14:15]
	global_load_dword v76, v[42:43], off offset:48 nt

; __device__ __forceinline__ void tconv_wave(const float* __restrict__ src, int ldsrc, int k0, int nsrc0, int nvalid,
;                                            u16* __restrict__ dst, int K, int ndst0, const float* __restrict__ gain, float* smw, int lane, int permg) {
;     ...
;     for (int i = 0; i < 32; i++) {
;       float t = 0.f;
;       if (lane < nvalid) {
;         t = src[(size_t)(k0 + kb + i) * ldsrc + nsrc0 + lane];
;         if (gain) t *= gain[k0 + kb + i];
;       }
;       v[i] = t;
;     }
.LBB0_84:
	s_or_b64 exec, exec, s[42:43]
	s_and_saveexec_b64 s[42:43], s[38:39]
	s_cbranch_execz .LBB0_88
	v_or_b32_e32 v39, 13, v22
	v_mul_lo_u32 v41, v17, v39
	v_mad_u64_u32 v[42:43], s[44:45], v16, v39, 0
	v_add3_u32 v43, v43, v6, v41
	v_lshl_add_u64 v[42:43], v[42:43], 2, v[20:21]
	global_load_dword v39, v[42:43], off nt
	s_and_saveexec_b64 s[44:45], s[6:7]
	s_cbranch_execz .LBB0_87
	v_lshl_add_u64 v[42:43], v[22:23], 2, v[14:15]
	global_load_dword v77, v[42:43], off offset:52 nt

; __device__ __forceinline__ void tconv_wave(const float* __restrict__ src, int ldsrc, int k0, int nsrc0, int nvalid,
;                                            u16* __restrict__ dst, int K, int ndst0, const float* __restrict__ gain, float* smw, int lane, int permg) {
;     ...
;     for (int i = 0; i < 32; i++) {
;       float t = 0.f;
;       if (lane < nvalid) {
;         t = src[(size_t)(k0 + kb + i) * ldsrc + nsrc0 + lane];
;         if (gain) t *= gain[k0 + kb + i];
;       }
;       v[i] = t;
;     }
.LBB0_88:
	s_or_b64 exec, exec, s[42:43]
	v_mov_b32_e32 v41, 0
	v_mov_b32_e32 v42, 0
	s_and_saveexec_b64 s[42:43], s[38:39]
	s_cbranch_execz .LBB0_92
	v_or_b32_e32 v42, 14, v22
	v_mul_lo_u32 v44, v17, v42
	v_mad_u64_u32 v[42:43], s[44:45], v16, v42, 0
	v_add3_u32 v43, v43, v6, v44
	v_lshl_add_u64 v[42:43], v[42:43], 2, v[20:21]
	global_load_dword v42, v[42:43], off nt
	s_and_saveexec_b64 s[44:45], s[6:7]
	s_cbranch_execz .LBB0_91
	v_lshl_add_u64 v[44:45], v[22:23], 2, v[14:15]
	global_load_dword v78, v[44:45], off offset:56 nt

; __device__ __forceinline__ void tconv_wave(const float* __restrict__ src, int ldsrc, int k0, int nsrc0, int nvalid,
;                                            u16* __restrict__ dst, int K, int ndst0, const float* __restrict__ gain, float* smw, int lane, int permg) {
;     ...
;     for (int i = 0; i < 32; i++) {
;       float t = 0.f;
;       if (lane < nvalid) {
;         t = src[(size_t)(k0 + kb + i) * ldsrc + nsrc0 + lane];
;         if (gain) t *= gain[k0 + kb + i];
;       }
;       v[i] = t;
;     }
.LBB0_92:
	s_or_b64 exec, exec, s[42:43]
	s_and_saveexec_b64 s[42:43], s[38:39]
	s_cbranch_execz .LBB0_96
	v_or_b32_e32 v41, 15, v22
	v_mul_lo_u32 v43, v17, v41
	v_mad_u64_u32 v[44:45], s[44:45], v16, v41, 0
	v_add3_u32 v45, v45, v6, v43
	v_lshl_add_u64 v[44:45], v[44:45], 2, v[20:21]
	global_load_dword v41, v[44:45], off nt
	s_and_saveexec_b64 s[44:45], s[6:7]
	s_cbranch_execz .LBB0_95
	v_lshl_add_u64 v[44:45], v[22:23], 2, v[14:15]
	global_load_dword v79, v[44:45], off offset:60 nt

; __device__ __forceinline__ void tconv_wave(const float* __restrict__ src, int ldsrc, int k0, int nsrc0, int nvalid,
;                                            u16* __restrict__ dst, int K, int ndst0, const float* __restrict__ gain, float* smw, int lane, int permg) {
;     ...
;     for (int i = 0; i < 32; i++) {
;       float t = 0.f;
;       if (lane < nvalid) {
;         t = src[(size_t)(k0 + kb + i) * ldsrc + nsrc0 + lane];
;         if (gain) t *= gain[k0 + kb + i];
;       }
;       v[i] = t;
;     }
.LBB0_96:
	s_or_b64 exec, exec, s[42:43]
	v_mov_b32_e32 v43, 0
	v_mov_b32_e32 v44, 0
	s_and_saveexec_b64 s[42:43], s[38:39]
	s_cbranch_execz .LBB0_100
	v_or_b32_e32 v44, 16, v22
	v_mul_lo_u32 v46, v17, v44
	v_mad_u64_u32 v[44:45], s[44:45], v16, v44, 0
	v_add3_u32 v45, v45, v6, v46
	v_lshl_add_u64 v[44:45], v[44:45], 2, v[20:21]
	global_load_dword v44, v[44:45], off nt
	s_and_saveexec_b64 s[44:45], s[6:7]
	s_cbranch_execz .LBB0_99
	v_lshl_add_u64 v[46:47], v[22:23], 2, v[14:15]
	global_load_dword v80, v[46:47], off offset:64 nt

; __device__ __forceinline__ void tconv_wave(const float* __restrict__ src, int ldsrc, int k0, int nsrc0, int nvalid,
;                                            u16* __restrict__ dst, int K, int ndst0, const float* __restrict__ gain, float* smw, int lane, int permg) {
;     ...
;     for (int i = 0; i < 32; i++) {
;       float t = 0.f;
;       if (lane < nvalid) {
;         t = src[(size_t)(k0 + kb + i) * ldsrc + nsrc0 + lane];
;         if (gain) t *= gain[k0 + kb + i];
;       }
;       v[i] = t;
;     }
.LBB0_100:
	s_or_b64 exec, exec, s[42:43]
	s_and_saveexec_b64 s[42:43], s[38:39]
	s_cbranch_execz .LBB0_104
	v_or_b32_e32 v43, 17, v22
	v_mul_lo_u32 v45, v17, v43
	v_mad_u64_u32 v[46:47], s[44:45], v16, v43, 0
	v_add3_u32 v47, v47, v6, v45
	v_lshl_add_u64 v[46:47], v[46:47], 2, v[20:21]
	global_load_dword v43, v[46:47], off nt
	s_and_saveexec_b64 s[44:45], s[6:7]
	s_cbranch_execz .LBB0_103
	v_lshl_add_u64 v[46:47], v[22:23], 2, v[14:15]
	global_load_dword v81, v[46:47], off offset:68 nt

; __device__ __forceinline__ void tconv_wave(const float* __restrict__ src, int ldsrc, int k0, int nsrc0, int nvalid,
;                                            u16* __restrict__ dst, int K, int ndst0, const float* __restrict__ gain, float* smw, int lane, int permg) {
;     ...
;     for (int i = 0; i < 32; i++) {
;       float t = 0.f;
;       if (lane < nvalid) {
;         t = src[(size_t)(k0 + kb + i) * ldsrc + nsrc0 + lane];
;         if (gain) t *= gain[k0 + kb + i];
;       }
;       v[i] = t;
;     }
.LBB0_104:
	s_or_b64 exec, exec, s[42:43]
	v_mov_b32_e32 v45, 0
	v_mov_b32_e32 v46, 0
	s_and_saveexec_b64 s[42:43], s[38:39]
	s_cbranch_execz .LBB0_108
	v_or_b32_e32 v46, 18, v22
	v_mul_lo_u32 v48, v17, v46
	v_mad_u64_u32 v[46:47], s[44:45], v16, v46, 0
	v_add3_u32 v47, v47, v6, v48
	v_lshl_add_u64 v[46:47], v[46:47], 2, v[20:21]
	global_load_dword v46, v[46:47], off nt
	s_and_saveexec_b64 s[44:45], s[6:7]
	s_cbranch_execz .LBB0_107
	v_lshl_add_u64 v[48:49], v[22:23], 2, v[14:15]
	global_load_dword v82, v[48:49], off offset:72 nt

; __device__ __forceinline__ void tconv_wave(const float* __restrict__ src, int ldsrc, int k0, int nsrc0, int nvalid,
;                                            u16* __restrict__ dst, int K, int ndst0, const float* __restrict__ gain, float* smw, int lane, int permg) {
;     ...
;     for (int i = 0; i < 32; i++) {
;       float t = 0.f;
;       if (lane < nvalid) {
;         t = src[(size_t)(k0 + kb + i) * ldsrc + nsrc0 + lane];
;         if (gain) t *= gain[k0 + kb + i];
;       }
;       v[i] = t;
;     }
.LBB0_108:
	s_or_b64 exec, exec, s[42:43]
	s_and_saveexec_b64 s[42:43], s[38:39]
	s_cbranch_execz .LBB0_112
	v_or_b32_e32 v45, 19, v22
	v_mul_lo_u32 v47, v17, v45
	v_mad_u64_u32 v[48:49], s[44:45], v16, v45, 0
	v_add3_u32 v49, v49, v6, v47
	v_lshl_add_u64 v[48:49], v[48:49], 2, v[20:21]
	global_load_dword v45, v[48:49], off nt
	s_and_saveexec_b64 s[44:45], s[6:7]
	s_cbranch_execz .LBB0_111
	v_lshl_add_u64 v[48:49], v[22:23], 2, v[14:15]
	global_load_dword v83, v[48:49], off offset:76 nt

; __device__ __forceinline__ void tconv_wave(const float* __restrict__ src, int ldsrc, int k0, int nsrc0, int nvalid,
;                                            u16* __restrict__ dst, int K, int ndst0, const float* __restrict__ gain, float* smw, int lane, int permg) {
;     ...
;     for (int i = 0; i < 32; i++) {
;       float t = 0.f;
;       if (lane < nvalid) {
;         t = src[(size_t)(k0 + kb + i) * ldsrc + nsrc0 + lane];
;         if (gain) t *= gain[k0 + kb + i];
;       }
;       v[i] = t;
;     }
.LBB0_112:
	s_or_b64 exec, exec, s[42:43]
	v_mov_b32_e32 v47, 0
	v_mov_b32_e32 v48, 0
	s_and_saveexec_b64 s[42:43], s[38:39]
	s_cbranch_execz .LBB0_116
	v_or_b32_e32 v48, 20, v22
	v_mul_lo_u32 v50, v17, v48
	v_mad_u64_u32 v[48:49], s[44:45], v16, v48, 0
	v_add3_u32 v49, v49, v6, v50
	v_lshl_add_u64 v[48:49], v[48:49], 2, v[20:21]
	global_load_dword v48, v[48:49], off nt
	s_and_saveexec_b64 s[44:45], s[6:7]
	s_cbranch_execz .LBB0_115
	v_lshl_add_u64 v[50:51], v[22:23], 2, v[14:15]
	global_load_dword v84, v[50:51], off offset:80 nt

; __device__ __forceinline__ void tconv_wave(const float* __restrict__ src, int ldsrc, int k0, int nsrc0, int nvalid,
;                                            u16* __restrict__ dst, int K, int ndst0, const float* __restrict__ gain, float* smw, int lane, int permg) {
;     ...
;     for (int i = 0; i < 32; i++) {
;       float t = 0.f;
;       if (lane < nvalid) {
;         t = src[(size_t)(k0 + kb + i) * ldsrc + nsrc0 + lane];
;         if (gain) t *= gain[k0 + kb + i];
;       }
;       v[i] = t;
;     }
.LBB0_116:
	s_or_b64 exec, exec, s[42:43]
	s_and_saveexec_b64 s[42:43], s[38:39]
	s_cbranch_execz .LBB0_120
	v_or_b32_e32 v47, 21, v22
	v_mul_lo_u32 v49, v17, v47
	v_mad_u64_u32 v[50:51], s[44:45], v16, v47, 0
	v_add3_u32 v51, v51, v6, v49
	v_lshl_add_u64 v[50:51], v[50:51], 2, v[20:21]
	global_load_dword v47, v[50:51], off nt
	s_and_saveexec_b64 s[44:45], s[6:7]
	s_cbranch_execz .LBB0_119
	v_lshl_add_u64 v[50:51], v[22:23], 2, v[14:15]
	global_load_dword v85, v[50:51], off offset:84 nt

; __device__ __forceinline__ void tconv_wave(const float* __restrict__ src, int ldsrc, int k0, int nsrc0, int nvalid,
;                                            u16* __restrict__ dst, int K, int ndst0, const float* __restrict__ gain, float* smw, int lane, int permg) {
;     ...
;     for (int i = 0; i < 32; i++) {
;       float t = 0.f;
;       if (lane < nvalid) {
;         t = src[(size_t)(k0 + kb + i) * ldsrc + nsrc0 + lane];
;         if (gain) t *= gain[k0 + kb + i];
;       }
;       v[i] = t;
;     }
.LBB0_120:
	s_or_b64 exec, exec, s[42:43]
	v_mov_b32_e32 v49, 0
	v_mov_b32_e32 v50, 0
	s_and_saveexec_b64 s[42:43], s[38:39]
	s_cbranch_execz .LBB0_124
	v_or_b32_e32 v50, 22, v22
	v_mul_lo_u32 v52, v17, v50
	v_mad_u64_u32 v[50:51], s[44:45], v16, v50, 0
	v_add3_u32 v51, v51, v6, v52
	v_lshl_add_u64 v[50:51], v[50:51], 2, v[20:21]
	global_load_dword v50, v[50:51], off nt
	s_and_saveexec_b64 s[44:45], s[6:7]
	s_cbranch_execz .LBB0_123
	v_lshl_add_u64 v[52:53], v[22:23], 2, v[14:15]
	global_load_dword v86, v[52:53], off offset:88 nt

; __device__ __forceinline__ void tconv_wave(const float* __restrict__ src, int ldsrc, int k0, int nsrc0, int nvalid,
;                                            u16* __restrict__ dst, int K, int ndst0, const float* __restrict__ gain, float* smw, int lane, int permg) {
;     ...
;     for (int i = 0; i < 32; i++) {
;       float t = 0.f;
;       if (lane < nvalid) {
;         t = src[(size_t)(k0 + kb + i) * ldsrc + nsrc0 + lane];
;         if (gain) t *= gain[k0 + kb + i];
;       }
;       v[i] = t;
;     }
.LBB0_124:
	s_or_b64 exec, exec, s[42:43]
	s_and_saveexec_b64 s[42:43], s[38:39]
	s_cbranch_execz .LBB0_128
	v_or_b32_e32 v49, 23, v22
	v_mul_lo_u32 v51, v17, v49
	v_mad_u64_u32 v[52:53], s[44:45], v16, v49, 0
	v_add3_u32 v53, v53, v6, v51
	v_lshl_add_u64 v[52:53], v[52:53], 2, v[20:21]
	global_load_dword v49, v[52:53], off nt
	s_and_saveexec_b64 s[44:45], s[6:7]
	s_cbranch_execz .LBB0_127
	v_lshl_add_u64 v[52:53], v[22:23], 2, v[14:15]
	global_load_dword v87, v[52:53], off offset:92 nt

; __device__ __forceinline__ void tconv_wave(const float* __restrict__ src, int ldsrc, int k0, int nsrc0, int nvalid,
;                                            u16* __restrict__ dst, int K, int ndst0, const float* __restrict__ gain, float* smw, int lane, int permg) {
;     ...
;     for (int i = 0; i < 32; i++) {
;       float t = 0.f;
;       if (lane < nvalid) {
;         t = src[(size_t)(k0 + kb + i) * ldsrc + nsrc0 + lane];
;         if (gain) t *= gain[k0 + kb + i];
;       }
;       v[i] = t;
;     }
.LBB0_128:
	s_or_b64 exec, exec, s[42:43]
	v_mov_b32_e32 v51, 0
	v_mov_b32_e32 v52, 0
	s_and_saveexec_b64 s[42:43], s[38:39]
	s_cbranch_execz .LBB0_132
	v_or_b32_e32 v52, 24, v22
	v_mul_lo_u32 v54, v17, v52
	v_mad_u64_u32 v[52:53], s[44:45], v16, v52, 0
	v_add3_u32 v53, v53, v6, v54
	v_lshl_add_u64 v[52:53], v[52:53], 2, v[20:21]
	global_load_dword v52, v[52:53], off nt
	s_and_saveexec_b64 s[44:45], s[6:7]
	s_cbranch_execz .LBB0_131
	v_lshl_add_u64 v[54:55], v[22:23], 2, v[14:15]
	global_load_dword v88, v[54:55], off offset:96 nt

; __device__ __forceinline__ void tconv_wave(const float* __restrict__ src, int ldsrc, int k0, int nsrc0, int nvalid,
;                                            u16* __restrict__ dst, int K, int ndst0, const float* __restrict__ gain, float* smw, int lane, int permg) {
;     ...
;     for (int i = 0; i < 32; i++) {
;       float t = 0.f;
;       if (lane < nvalid) {
;         t = src[(size_t)(k0 + kb + i) * ldsrc + nsrc0 + lane];
;         if (gain) t *= gain[k0 + kb + i];
;       }
;       v[i] = t;
;     }
.LBB0_132:
	s_or_b64 exec, exec, s[42:43]
	s_and_saveexec_b64 s[42:43], s[38:39]
	s_cbranch_execz .LBB0_136
	v_or_b32_e32 v51, 25, v22
	v_mul_lo_u32 v53, v17, v51
	v_mad_u64_u32 v[54:55], s[44:45], v16, v51, 0
	v_add3_u32 v55, v55, v6, v53
	v_lshl_add_u64 v[54:55], v[54:55], 2, v[20:21]
	global_load_dword v51, v[54:55], off nt
	s_and_saveexec_b64 s[44:45], s[6:7]
	s_cbranch_execz .LBB0_135
	v_lshl_add_u64 v[54:55], v[22:23], 2, v[14:15]
	global_load_dword v89, v[54:55], off offset:100 nt

; __device__ __forceinline__ void tconv_wave(const float* __restrict__ src, int ldsrc, int k0, int nsrc0, int nvalid,
;                                            u16* __restrict__ dst, int K, int ndst0, const float* __restrict__ gain, float* smw, int lane, int permg) {
;     ...
;     for (int i = 0; i < 32; i++) {
;       float t = 0.f;
;       if (lane < nvalid) {
;         t = src[(size_t)(k0 + kb + i) * ldsrc + nsrc0 + lane];
;         if (gain) t *= gain[k0 + kb + i];
;       }
;       v[i] = t;
;     }
.LBB0_136:
	s_or_b64 exec, exec, s[42:43]
	v_mov_b32_e32 v53, 0
	v_mov_b32_e32 v54, 0
	s_and_saveexec_b64 s[42:43], s[38:39]
	s_cbranch_execz .LBB0_140
	v_or_b32_e32 v54, 26, v22
	v_mul_lo_u32 v56, v17, v54
	v_mad_u64_u32 v[54:55], s[44:45], v16, v54, 0
	v_add3_u32 v55, v55, v6, v56
	v_lshl_add_u64 v[54:55], v[54:55], 2, v[20:21]
	global_load_dword v54, v[54:55], off nt
	s_and_saveexec_b64 s[44:45], s[6:7]
	s_cbranch_execz .LBB0_139
	v_lshl_add_u64 v[56:57], v[22:23], 2, v[14:15]
	global_load_dword v90, v[56:57], off offset:104 nt

; __device__ __forceinline__ void tconv_wave(const float* __restrict__ src, int ldsrc, int k0, int nsrc0, int nvalid,
;                                            u16* __restrict__ dst, int K, int ndst0, const float* __restrict__ gain, float* smw, int lane, int permg) {
;     ...
;     for (int i = 0; i < 32; i++) {
;       float t = 0.f;
;       if (lane < nvalid) {
;         t = src[(size_t)(k0 + kb + i) * ldsrc + nsrc0 + lane];
;         if (gain) t *= gain[k0 + kb + i];
;       }
;       v[i] = t;
;     }
.LBB0_140:
	s_or_b64 exec, exec, s[42:43]
	s_and_saveexec_b64 s[42:43], s[38:39]
	s_cbranch_execz .LBB0_144
	v_or_b32_e32 v53, 27, v22
	v_mul_lo_u32 v55, v17, v53
	v_mad_u64_u32 v[56:57], s[44:45], v16, v53, 0
	v_add3_u32 v57, v57, v6, v55
	v_lshl_add_u64 v[56:57], v[56:57], 2, v[20:21]
	global_load_dword v53, v[56:57], off nt
	s_and_saveexec_b64 s[44:45], s[6:7]
	s_cbranch_execz .LBB0_143
	v_lshl_add_u64 v[56:57], v[22:23], 2, v[14:15]
	global_load_dword v91, v[56:57], off offset:108 nt

; __device__ __forceinline__ void tconv_wave(const float* __restrict__ src, int ldsrc, int k0, int nsrc0, int nvalid,
;                                            u16* __restrict__ dst, int K, int ndst0, const float* __restrict__ gain, float* smw, int lane, int permg) {
;     ...
;     for (int i = 0; i < 32; i++) {
;       float t = 0.f;
;       if (lane < nvalid) {
;         t = src[(size_t)(k0 + kb + i) * ldsrc + nsrc0 + lane];
;         if (gain) t *= gain[k0 + kb + i];
;       }
;       v[i] = t;
;     }
.LBB0_144:
	s_or_b64 exec, exec, s[42:43]
	v_mov_b32_e32 v55, 0
	v_mov_b32_e32 v56, 0
	s_and_saveexec_b64 s[42:43], s[38:39]
	s_cbranch_execz .LBB0_148
	v_or_b32_e32 v56, 28, v22
	v_mul_lo_u32 v58, v17, v56
	v_mad_u64_u32 v[56:57], s[44:45], v16, v56, 0
	v_add3_u32 v57, v57, v6, v58
	v_lshl_add_u64 v[56:57], v[56:57], 2, v[20:21]
	global_load_dword v56, v[56:57], off nt
	s_and_saveexec_b64 s[44:45], s[6:7]
	s_cbranch_execz .LBB0_147
	v_lshl_add_u64 v[58:59], v[22:23], 2, v[14:15]
	global_load_dword v92, v[58:59], off offset:112 nt

; __device__ __forceinline__ void tconv_wave(const float* __restrict__ src, int ldsrc, int k0, int nsrc0, int nvalid,
;                                            u16* __restrict__ dst, int K, int ndst0, const float* __restrict__ gain, float* smw, int lane, int permg) {
;     ...
;     for (int i = 0; i < 32; i++) {
;       float t = 0.f;
;       if (lane < nvalid) {
;         t = src[(size_t)(k0 + kb + i) * ldsrc + nsrc0 + lane];
;         if (gain) t *= gain[k0 + kb + i];
;       }
;       v[i] = t;
;     }
.LBB0_148:
	s_or_b64 exec, exec, s[42:43]
	s_and_saveexec_b64 s[42:43], s[38:39]
	s_cbranch_execz .LBB0_152
	v_or_b32_e32 v55, 29, v22
	v_mul_lo_u32 v57, v17, v55
	v_mad_u64_u32 v[58:59], s[44:45], v16, v55, 0
	v_add3_u32 v59, v59, v6, v57
	v_lshl_add_u64 v[58:59], v[58:59], 2, v[20:21]
	global_load_dword v55, v[58:59], off nt
	s_and_saveexec_b64 s[44:45], s[6:7]
	s_cbranch_execz .LBB0_151
	v_lshl_add_u64 v[58:59], v[22:23], 2, v[14:15]
	global_load_dword v93, v[58:59], off offset:116 nt

; __device__ __forceinline__ void tconv_wave(const float* __restrict__ src, int ldsrc, int k0, int nsrc0, int nvalid,
;                                            u16* __restrict__ dst, int K, int ndst0, const float* __restrict__ gain, float* smw, int lane, int permg) {
;     ...
;     for (int i = 0; i < 32; i++) {
;       float t = 0.f;
;       if (lane < nvalid) {
;         t = src[(size_t)(k0 + kb + i) * ldsrc + nsrc0 + lane];
;         if (gain) t *= gain[k0 + kb + i];
;       }
;       v[i] = t;
;     }
.LBB0_152:
	s_or_b64 exec, exec, s[42:43]
	v_mov_b32_e32 v57, 0
	v_mov_b32_e32 v58, 0
	s_and_saveexec_b64 s[42:43], s[38:39]
	s_cbranch_execz .LBB0_156
	v_or_b32_e32 v58, 30, v22
	v_mul_lo_u32 v60, v17, v58
	v_mad_u64_u32 v[58:59], s[44:45], v16, v58, 0
	v_add3_u32 v59, v59, v6, v60
	v_lshl_add_u64 v[58:59], v[58:59], 2, v[20:21]
	global_load_dword v58, v[58:59], off nt
	s_and_saveexec_b64 s[44:45], s[6:7]
	s_cbranch_execz .LBB0_155
	v_lshl_add_u64 v[60:61], v[22:23], 2, v[14:15]
	global_load_dword v94, v[60:61], off offset:120 nt

; __device__ __forceinline__ void tconv_wave(const float* __restrict__ src, int ldsrc, int k0, int nsrc0, int nvalid,
;                                            u16* __restrict__ dst, int K, int ndst0, const float* __restrict__ gain, float* smw, int lane, int permg) {
;     ...
;     for (int i = 0; i < 32; i++) {
;       float t = 0.f;
;       if (lane < nvalid) {
;         t = src[(size_t)(k0 + kb + i) * ldsrc + nsrc0 + lane];
;         if (gain) t *= gain[k0 + kb + i];
;       }
;       v[i] = t;
;     }
.LBB0_156:
	s_or_b64 exec, exec, s[42:43]
	s_and_saveexec_b64 s[42:43], s[38:39]
	s_cbranch_execz .LBB0_31
	v_or_b32_e32 v57, 31, v22
	v_mul_lo_u32 v59, v17, v57
	v_mad_u64_u32 v[60:61], s[44:45], v16, v57, 0
	v_add3_u32 v61, v61, v6, v59
	v_lshl_add_u64 v[60:61], v[60:61], 2, v[20:21]
	global_load_dword v57, v[60:61], off nt
	s_and_saveexec_b64 s[44:45], s[6:7]
	s_cbranch_execz .LBB0_30
	v_lshl_add_u64 v[22:23], v[22:23], 2, v[14:15]
	global_load_dword v95, v[22:23], off offset:124 nt
	s_branch .LBB0_30

; __device__ void phase0(const Params& p, unsigned char* smem) {
;     ...
; #pragma unroll 2
;     for (size_t i4 = gtid; i4 < (size_t)8 * 1024 * 512 / 4; i4 += gsz) {
;       const size_t i = i4 * 4;
;       int d = (int)(i & 63), hd = (int)((i >> 6) & 7), j = (int)((i >> 9) & 1023), bs = (int)(i >> 19);
;       const float4 kk4 = *(const float4*)(cka + i);
;       const float4 vv4 = *(const float4*)(cva + i);
;       uint2 ko; ko.x = pack2(kk4.x, kk4.y); ko.y = pack2(kk4.z, kk4.w);
;       *(uint2*)(KAS + ((size_t)(bs * 8 + hd) * 1088 + j) * 64 + d) = ko;
;       u16* vd = VAS + (size_t)(bs * 8 + hd) * 64 * 1088 + (size_t)(j >> 6) * 4096 + d * 64 + (j & 63);
;       vd[0] = f2bf(vv4.x); vd[64] = f2bf(vv4.y); vd[2 * 64] = f2bf(vv4.z); vd[3 * 64] = f2bf(vv4.w);
;     }
.LBB0_189:
	s_or_b64 exec, exec, s[4:5]
	s_add_u32 s4, s88, 0x165a4800
	s_addc_u32 s5, s89, 0
	v_lshl_add_u64 v[8:9], v[12:13], 0, v[8:9]
	s_add_u32 s10, s88, 0x18e24800
	v_and_b32_e32 v10, 1, v8
	v_mov_b32_e32 v11, 0
	s_addc_u32 s11, s89, 0
	v_cmp_eq_u64_e32 vcc, 0, v[10:11]
	v_mov_b64_e32 v[40:41], v[4:5]
	s_and_saveexec_b64 s[8:9], vcc
	s_cbranch_execz .LBB0_191
	s_load_dwordx16 s[12:27], s[92:93], 0x0
	v_lshlrev_b64 v[16:17], 4, v[4:5]
	v_bfe_u32 v10, v4, 4, 3
	v_lshrrev_b32_e32 v23, 14, v4
	v_and_or_b32 v10, v23, 56, v10
	s_waitcnt lgkmcnt(0)
	v_lshl_add_u64 v[12:13], s[16:17], 0, v[16:17]
	v_lshl_add_u64 v[16:17], s[18:19], 0, v[16:17]
	global_load_dwordx4 v[12:15], v[12:13], off nt
	v_bfe_u32 v22, v4, 7, 10
	global_load_dwordx4 v[16:19], v[16:17], off nt
	s_mov_b32 s0, 0x22000
	v_mov_b64_e32 v[20:21], s[10:11]
	v_mul_u32_u24_e32 v23, 0x440, v10
	v_lshlrev_b32_e32 v24, 3, v4
	v_mad_u64_u32 v[20:21], s[0:1], v10, s0, v[20:21]
	v_add_lshl_u32 v10, v23, v22, 7
	v_lshl_add_u64 v[22:23], s[4:5], 0, v[10:11]
	v_and_b32_e32 v10, 0x78, v24
	v_lshlrev_b32_e32 v25, 9, v4
	v_lshl_add_u64 v[22:23], v[22:23], 0, v[10:11]
	v_and_b32_e32 v10, 0x1e000, v4
	v_lshrrev_b32_e32 v26, 6, v4
	v_lshl_add_u64 v[20:21], v[20:21], 0, v[10:11]
	v_and_b32_e32 v10, 0x1e00, v25
	s_movk_i32 s3, 0x7fff
	v_lshl_add_u64 v[20:21], v[20:21], 0, v[10:11]
	v_and_b32_e32 v10, 0x7e, v26
	v_lshl_add_u64 v[10:11], v[20:21], 0, v[10:11]
	v_lshl_add_u64 v[40:41], v[4:5], 0, v[2:3]
	s_waitcnt vmcnt(1)
	v_cvt_pk_bf16_f32 v12, v12, v13
	v_cvt_pk_bf16_f32 v13, v14, v15
	s_waitcnt vmcnt(0)
	v_bfe_u32 v14, v16, 16, 1
	v_bfe_u32 v15, v17, 16, 1
	v_bfe_u32 v20, v18, 16, 1
	v_bfe_u32 v21, v19, 16, 1
	global_store_dwordx2 v[22:23], v[12:13], off
	v_add3_u32 v12, v16, v14, s3
	v_add3_u32 v13, v17, v15, s3
	v_add3_u32 v14, v18, v20, s3
	v_add3_u32 v15, v19, v21, s3
	global_store_short_d16_hi v[10:11], v12, off
	global_store_short_d16_hi v[10:11], v13, off offset:128
	global_store_short_d16_hi v[10:11], v14, off offset:256
	global_store_short_d16_hi v[10:11], v15, off offset:384

; __device__ void phase0(const Params& p, unsigned char* smem) {
;     ...
; #pragma unroll 2
;     for (size_t i4 = gtid; i4 < (size_t)8 * 1024 * 512 / 4; i4 += gsz) {
;       const size_t i = i4 * 4;
;       int d = (int)(i & 63), hd = (int)((i >> 6) & 7), j = (int)((i >> 9) & 1023), bs = (int)(i >> 19);
;       const float4 kk4 = *(const float4*)(cka + i);
;       const float4 vv4 = *(const float4*)(cva + i);
;       uint2 ko; ko.x = pack2(kk4.x, kk4.y); ko.y = pack2(kk4.z, kk4.w);
;       *(uint2*)(KAS + ((size_t)(bs * 8 + hd) * 1088 + j) * 64 + d) = ko;
;       u16* vd = VAS + (size_t)(bs * 8 + hd) * 64 * 1088 + (size_t)(j >> 6) * 4096 + d * 64 + (j & 63);
;       vd[0] = f2bf(vv4.x); vd[64] = f2bf(vv4.y); vd[2 * 64] = f2bf(vv4.z); vd[3 * 64] = f2bf(vv4.w);
;     }
.LBB0_193:
	v_lshl_add_u64 v[54:55], v[20:21], 0, v[30:31]
	v_lshl_add_u64 v[52:53], v[28:29], 0, v[30:31]
	global_load_dwordx4 v[44:47], v[54:55], off nt
	global_load_dwordx4 v[48:51], v[52:53], off nt
	v_bfe_u32 v15, v40, 4, 3
	v_lshrrev_b32_e32 v39, 14, v40
	v_and_or_b32 v15, v39, 56, v15
	v_bfe_u32 v32, v40, 7, 10
	v_mul_u32_u24_e32 v39, 0x440, v15
	v_and_b32_e32 v43, 60, v16
	v_add_lshl_u32 v32, v39, v32, 7
	v_lshl_add_u64 v[58:59], s[4:5], 0, v[32:33]
	v_lshlrev_b32_e32 v32, 1, v43
	v_and_b32_e32 v60, 0xf00, v10
	v_mad_u64_u32 v[56:57], s[12:13], v15, s0, v[34:35]
	v_lshl_add_u64 v[58:59], v[58:59], 0, v[32:33]
	v_and_b32_e32 v32, 0x1e000, v40
	v_lshrrev_b32_e32 v61, 6, v40
	v_lshl_add_u64 v[56:57], v[56:57], 0, v[32:33]
	v_lshlrev_b32_e32 v32, 1, v60
	v_lshl_add_u64 v[56:57], v[56:57], 0, v[32:33]
	v_and_b32_e32 v32, 0x7e, v61
	v_lshl_add_u64 v[56:57], v[56:57], 0, v[32:33]
	v_lshl_add_u64 v[54:55], v[24:25], 0, v[30:31]
	v_lshl_add_u64 v[52:53], v[26:27], 0, v[30:31]
	v_lshl_add_u64 v[30:31], v[30:31], 0, v[22:23]
	global_load_dwordx4 v[62:65], v[54:55], off nt
	global_load_dwordx4 v[66:69], v[52:53], off nt
	s_waitcnt vmcnt(3)
	v_bfe_u32 v15, v44, 16, 1
	s_waitcnt vmcnt(2)
	v_cvt_pk_bf16_f32 v48, v48, v49
	v_cvt_pk_bf16_f32 v49, v50, v51
	v_bfe_u32 v32, v45, 16, 1
	v_bfe_u32 v39, v46, 16, 1
	v_bfe_u32 v43, v47, 16, 1
	v_add3_u32 v15, v44, v15, s1
	global_store_dwordx2 v[58:59], v[48:49], off
	v_add3_u32 v32, v45, v32, s1
	v_add3_u32 v39, v46, v39, s1
	v_add3_u32 v43, v47, v43, s1
	global_store_short_d16_hi v[56:57], v15, off
	global_store_short_d16_hi v[56:57], v32, off offset:128
	global_store_short_d16_hi v[56:57], v39, off offset:256
	global_store_short_d16_hi v[56:57], v43, off offset:384
	v_lshl_add_u64 v[52:53], v[40:41], 0, v[2:3]
	v_add_u32_e32 v39, v9, v40
	v_add_u32_e32 v32, v8, v10
	v_bfe_u32 v40, v52, 4, 3
	v_lshrrev_b32_e32 v41, 14, v52
	v_and_b32_e32 v56, 0xf00, v32
	v_and_or_b32 v32, v41, 56, v40
	v_add_u32_e32 v15, v14, v16
	v_bfe_u32 v43, v39, 7, 10
	v_mul_u32_u24_e32 v58, 0x440, v32
	v_and_b32_e32 v15, 60, v15
	v_mad_u64_u32 v[54:55], s[12:13], v32, s0, v[34:35]
	v_add_lshl_u32 v32, v58, v43, 7
	v_lshl_add_u64 v[40:41], v[52:53], 0, v[2:3]
	v_lshl_add_u64 v[52:53], s[4:5], 0, v[32:33]
	v_lshlrev_b32_e32 v32, 1, v15
	v_lshl_add_u64 v[52:53], v[52:53], 0, v[32:33]
	v_and_b32_e32 v32, 0x1e000, v39
	v_lshrrev_b32_e32 v57, 6, v39
	v_lshl_add_u64 v[54:55], v[54:55], 0, v[32:33]
	v_lshlrev_b32_e32 v32, 1, v56
	v_cmp_lt_u64_e32 vcc, s[10:11], v[40:41]
	v_lshl_add_u64 v[54:55], v[54:55], 0, v[32:33]
	v_and_b32_e32 v32, 0x7e, v57
	v_lshl_add_u64 v[10:11], v[10:11], 0, v[12:13]
	v_lshl_add_u64 v[16:17], v[16:17], 0, v[18:19]
	s_or_b64 s[8:9], vcc, s[8:9]
	v_lshl_add_u64 v[54:55], v[54:55], 0, v[32:33]
	s_waitcnt vmcnt(6)
	v_bfe_u32 v15, v62, 16, 1
	s_waitcnt vmcnt(5)
	v_cvt_pk_bf16_f32 v66, v66, v67
	v_cvt_pk_bf16_f32 v67, v68, v69
	v_bfe_u32 v32, v63, 16, 1
	v_bfe_u32 v39, v64, 16, 1
	v_bfe_u32 v43, v65, 16, 1
	v_add3_u32 v15, v62, v15, s1
	global_store_dwordx2 v[52:53], v[66:67], off
	v_add3_u32 v32, v63, v32, s1
	v_add3_u32 v39, v64, v39, s1
	v_add3_u32 v43, v65, v43, s1
	global_store_short_d16_hi v[54:55], v15, off
	global_store_short_d16_hi v[54:55], v32, off offset:128
	global_store_short_d16_hi v[54:55], v39, off offset:256
	global_store_short_d16_hi v[54:55], v43, off offset:384
	s_andn2_b64 exec, exec, s[8:9]
	s_cbranch_execnz .LBB0_193

; __device__ void phase0(const Params& p, unsigned char* smem) {
;     ...
;     for (size_t i4 = gtid; i4 < (size_t)8 * 1024 * 64 / 4; i4 += gsz) {
;       const size_t i = i4 * 4;
;       int d = (int)(i & 63), j = (int)((i >> 6) & 1023), bs = (int)(i >> 16);
;       const float4 kk4 = *(const float4*)(cki + i);
;       uint2 ko; ko.x = pack2(kk4.x, kk4.y); ko.y = pack2(kk4.z, kk4.w);
;       *(uint2*)(KIS + ((size_t)bs * 1088 + j) * 64 + d) = ko;
;     }
.LBB0_196:
	global_load_dwordx4 v[20:23], v[8:9], off offset:-8 nt
	v_alignbit_b32 v24, v19, v18, 14
	v_bfe_u32 v16, v18, 4, 10
	v_mul_hi_i32_i24_e32 v25, 0x440, v24
	v_mul_i32_i24_e32 v24, 0x440, v24
	v_lshl_add_u64 v[24:25], v[24:25], 0, v[16:17]
	v_and_b32_e32 v26, 60, v12
	v_lshl_add_u64 v[18:19], v[18:19], 0, v[2:3]
	v_lshlrev_b64 v[24:25], 7, v[24:25]
	v_cmp_lt_u64_e32 vcc, s[10:11], v[18:19]
	v_lshlrev_b32_e32 v16, 1, v26
	v_lshl_add_u64 v[24:25], s[6:7], 0, v[24:25]
	v_lshl_add_u64 v[8:9], v[8:9], 0, v[10:11]
	v_lshl_add_u64 v[12:13], v[12:13], 0, v[14:15]
	s_or_b64 s[8:9], vcc, s[8:9]
	v_lshl_add_u64 v[24:25], v[24:25], 0, v[16:17]
	s_waitcnt vmcnt(0)
	v_cvt_pk_bf16_f32 v20, v20, v21
	v_cvt_pk_bf16_f32 v21, v22, v23
	global_store_dwordx2 v[24:25], v[20:21], off
	s_andn2_b64 exec, exec, s[8:9]
	s_cbranch_execnz .LBB0_196

; __device__ void phase0(const Params& p, unsigned char* smem) {
;     ...
; #pragma unroll 2
;     for (size_t i4 = gtid; i4 < (size_t)8 * 512 * 512 / 4; i4 += gsz) {
;       const size_t i = i4 * 4;
;       int d = (int)(i & 63), hd = (int)((i >> 6) & 7), j = (int)((i >> 9) & 511), bs = (int)(i >> 18);
;       const float4 kk4 = *(const float4*)(ckb + i);
;       const float4 vv4 = *(const float4*)(cvb + i);
;       uint2 ko; ko.x = pack2(kk4.x, kk4.y); ko.y = pack2(kk4.z, kk4.w);
;       *(uint2*)(KBS + ((size_t)(bs * 8 + hd) * 576 + j) * 64 + d) = ko;
;       u16* vd = VBS + (size_t)(bs * 8 + hd) * 64 * 576 + (size_t)(j >> 6) * 4096 + d * 64 + (j & 63);
;       vd[0] = f2bf(vv4.x); vd[64] = f2bf(vv4.y); vd[2 * 64] = f2bf(vv4.z); vd[3 * 64] = f2bf(vv4.w);
;     }
.LBB0_202:
	s_or_b64 exec, exec, s[4:5]
	s_add_u32 s4, s88, 0x1bbb4800
	s_addc_u32 s5, s89, 0
	v_lshl_add_u64 v[6:7], v[10:11], 0, v[6:7]
	s_add_u32 s10, s88, 0x1e034800
	v_and_b32_e32 v8, 1, v6
	v_mov_b32_e32 v9, 0
	s_addc_u32 s11, s89, 0
	v_cmp_eq_u64_e32 vcc, 0, v[8:9]
	s_and_saveexec_b64 s[8:9], vcc
	s_cbranch_execz .LBB0_204
	s_load_dwordx16 s[12:27], s[92:93], 0x0
	v_lshlrev_b64 v[14:15], 4, v[4:5]
	v_bfe_u32 v8, v4, 4, 3
	v_lshrrev_b32_e32 v21, 13, v4
	v_and_or_b32 v8, v21, 56, v8
	s_waitcnt lgkmcnt(0)
	v_lshl_add_u64 v[10:11], s[22:23], 0, v[14:15]
	v_lshl_add_u64 v[14:15], s[24:25], 0, v[14:15]
	global_load_dwordx4 v[10:13], v[10:11], off nt
	v_bfe_u32 v20, v4, 7, 9
	global_load_dwordx4 v[14:17], v[14:15], off nt
	s_mov_b32 s0, 0x12000
	v_mov_b64_e32 v[18:19], s[10:11]
	v_mul_u32_u24_e32 v21, 0x240, v8
	v_lshlrev_b32_e32 v22, 3, v4
	v_mad_u64_u32 v[18:19], s[0:1], v8, s0, v[18:19]
	v_add_lshl_u32 v8, v21, v20, 7
	v_lshl_add_u64 v[20:21], s[4:5], 0, v[8:9]
	v_and_b32_e32 v8, 0x78, v22
	v_lshlrev_b32_e32 v23, 9, v4
	v_lshl_add_u64 v[20:21], v[20:21], 0, v[8:9]
	v_and_b32_e32 v8, 0xe000, v4
	v_lshrrev_b32_e32 v24, 6, v4
	v_lshl_add_u64 v[18:19], v[18:19], 0, v[8:9]
	v_and_b32_e32 v8, 0x1e00, v23
	s_movk_i32 s3, 0x7fff
	v_lshl_add_u64 v[18:19], v[18:19], 0, v[8:9]
	v_and_b32_e32 v8, 0x7e, v24
	v_lshl_add_u64 v[8:9], v[18:19], 0, v[8:9]
	v_lshl_add_u64 v[4:5], v[4:5], 0, v[2:3]
	s_waitcnt vmcnt(1)
	v_cvt_pk_bf16_f32 v10, v10, v11
	v_cvt_pk_bf16_f32 v11, v12, v13
	s_waitcnt vmcnt(0)
	v_bfe_u32 v12, v14, 16, 1
	v_bfe_u32 v13, v15, 16, 1
	v_bfe_u32 v18, v16, 16, 1
	v_bfe_u32 v19, v17, 16, 1
	global_store_dwordx2 v[20:21], v[10:11], off
	v_add3_u32 v10, v14, v12, s3
	v_add3_u32 v11, v15, v13, s3
	v_add3_u32 v12, v16, v18, s3
	v_add3_u32 v13, v17, v19, s3
	global_store_short_d16_hi v[8:9], v10, off
	global_store_short_d16_hi v[8:9], v11, off offset:128
	global_store_short_d16_hi v[8:9], v12, off offset:256
	global_store_short_d16_hi v[8:9], v13, off offset:384

; __device__ void phase0(const Params& p, unsigned char* smem) {
;     ...
; #pragma unroll 2
;     for (size_t i4 = gtid; i4 < (size_t)8 * 512 * 512 / 4; i4 += gsz) {
;       const size_t i = i4 * 4;
;       int d = (int)(i & 63), hd = (int)((i >> 6) & 7), j = (int)((i >> 9) & 511), bs = (int)(i >> 18);
;       const float4 kk4 = *(const float4*)(ckb + i);
;       const float4 vv4 = *(const float4*)(cvb + i);
;       uint2 ko; ko.x = pack2(kk4.x, kk4.y); ko.y = pack2(kk4.z, kk4.w);
;       *(uint2*)(KBS + ((size_t)(bs * 8 + hd) * 576 + j) * 64 + d) = ko;
;       u16* vd = VBS + (size_t)(bs * 8 + hd) * 64 * 576 + (size_t)(j >> 6) * 4096 + d * 64 + (j & 63);
;       vd[0] = f2bf(vv4.x); vd[64] = f2bf(vv4.y); vd[2 * 64] = f2bf(vv4.z); vd[3 * 64] = f2bf(vv4.w);
;     }
.LBB0_206:
	v_lshl_add_u64 v[46:47], v[18:19], 0, v[28:29]
	v_lshl_add_u64 v[34:35], v[26:27], 0, v[28:29]
	global_load_dwordx4 v[38:41], v[46:47], off nt
	global_load_dwordx4 v[42:45], v[34:35], off nt
	v_bfe_u32 v7, v4, 4, 3
	v_lshrrev_b32_e32 v30, 13, v4
	v_and_or_b32 v7, v30, 56, v7
	v_bfe_u32 v13, v4, 7, 9
	v_mul_u32_u24_e32 v30, 0x240, v7
	v_and_b32_e32 v37, 60, v14
	v_add_lshl_u32 v30, v30, v13, 7
	v_lshl_add_u64 v[50:51], s[4:5], 0, v[30:31]
	v_lshlrev_b32_e32 v30, 1, v37
	v_and_b32_e32 v52, 0xf00, v8
	v_mad_u64_u32 v[48:49], s[12:13], v7, s0, v[32:33]
	v_lshl_add_u64 v[50:51], v[50:51], 0, v[30:31]
	v_and_b32_e32 v30, 0xe000, v4
	v_lshrrev_b32_e32 v53, 6, v4
	v_lshl_add_u64 v[48:49], v[48:49], 0, v[30:31]
	v_lshlrev_b32_e32 v30, 1, v52
	v_lshl_add_u64 v[48:49], v[48:49], 0, v[30:31]
	v_and_b32_e32 v30, 0x7e, v53
	v_lshl_add_u64 v[48:49], v[48:49], 0, v[30:31]
	v_lshl_add_u64 v[46:47], v[22:23], 0, v[28:29]
	v_lshl_add_u64 v[34:35], v[24:25], 0, v[28:29]
	v_lshl_add_u64 v[28:29], v[28:29], 0, v[20:21]
	global_load_dwordx4 v[62:65], v[46:47], off nt
	global_load_dwordx4 v[66:69], v[34:35], off nt
	s_waitcnt vmcnt(3)
	v_bfe_u32 v7, v38, 16, 1
	s_waitcnt vmcnt(2)
	v_cvt_pk_bf16_f32 v42, v42, v43
	v_cvt_pk_bf16_f32 v43, v44, v45
	v_bfe_u32 v13, v39, 16, 1
	v_bfe_u32 v30, v40, 16, 1
	v_bfe_u32 v37, v41, 16, 1
	v_add3_u32 v7, v38, v7, s1
	global_store_dwordx2 v[50:51], v[42:43], off
	v_add3_u32 v13, v39, v13, s1
	v_add3_u32 v30, v40, v30, s1
	v_add3_u32 v37, v41, v37, s1
	global_store_short_d16_hi v[48:49], v7, off
	global_store_short_d16_hi v[48:49], v13, off offset:128
	global_store_short_d16_hi v[48:49], v30, off offset:256
	global_store_short_d16_hi v[48:49], v37, off offset:384
	v_lshl_add_u64 v[34:35], v[4:5], 0, v[2:3]
	v_add_u32_e32 v7, v1, v4
	v_add_u32_e32 v4, v6, v8
	v_bfe_u32 v13, v34, 4, 3
	v_lshrrev_b32_e32 v37, 13, v34
	v_and_b32_e32 v49, 0xf00, v4
	v_and_or_b32 v4, v37, 56, v13
	v_add_u32_e32 v5, v12, v14
	v_bfe_u32 v30, v7, 7, 9
	v_mul_u32_u24_e32 v13, 0x240, v4
	v_and_b32_e32 v48, 60, v5
	v_add_lshl_u32 v30, v13, v30, 7
	v_mad_u64_u32 v[46:47], s[12:13], v4, s0, v[32:33]
	v_lshl_add_u64 v[4:5], v[34:35], 0, v[2:3]
	v_lshl_add_u64 v[34:35], s[4:5], 0, v[30:31]
	v_lshlrev_b32_e32 v30, 1, v48
	v_lshl_add_u64 v[34:35], v[34:35], 0, v[30:31]
	v_and_b32_e32 v30, 0xe000, v7
	v_lshrrev_b32_e32 v50, 6, v7
	v_lshl_add_u64 v[46:47], v[46:47], 0, v[30:31]
	v_lshlrev_b32_e32 v30, 1, v49
	v_cmp_lt_u64_e32 vcc, s[10:11], v[4:5]
	v_lshl_add_u64 v[46:47], v[46:47], 0, v[30:31]
	v_and_b32_e32 v30, 0x7e, v50
	v_lshl_add_u64 v[8:9], v[8:9], 0, v[10:11]
	v_lshl_add_u64 v[14:15], v[14:15], 0, v[16:17]
	s_or_b64 s[8:9], vcc, s[8:9]
	v_lshl_add_u64 v[46:47], v[46:47], 0, v[30:31]
	s_waitcnt vmcnt(6)
	v_bfe_u32 v7, v62, 16, 1
	s_waitcnt vmcnt(5)
	v_cvt_pk_bf16_f32 v66, v66, v67
	v_cvt_pk_bf16_f32 v67, v68, v69
	v_bfe_u32 v13, v63, 16, 1
	v_bfe_u32 v30, v64, 16, 1
	v_bfe_u32 v37, v65, 16, 1
	v_add3_u32 v7, v62, v7, s1
	global_store_dwordx2 v[34:35], v[66:67], off
	v_add3_u32 v13, v63, v13, s1
	v_add3_u32 v30, v64, v30, s1
	v_add3_u32 v34, v65, v37, s1
	global_store_short_d16_hi v[46:47], v7, off
	global_store_short_d16_hi v[46:47], v13, off offset:128
	global_store_short_d16_hi v[46:47], v30, off offset:256
	global_store_short_d16_hi v[46:47], v34, off offset:384
	s_andn2_b64 exec, exec, s[8:9]
	s_cbranch_execnz .LBB0_206
